# v89 stack plus de-serialised small tails (P3tt, pooltt, P5tt, P5g8): loads hoisted ahead of the MFMA chain
# speedup vs baseline: 1.0035x; 1.0024x over previous
.LBB0_348:
	v_ashrrev_i32_e32 v22, 4, v6
	v_ashrrev_i32_e32 v23, 31, v22
	v_lshlrev_b64 v[12:13], 17, v[22:23]
	v_and_b32_e32 v23, 0xf0, v9
	v_lshlrev_b32_e32 v10, 7, v22
	v_or_b32_e32 v5, v23, v7
	v_ashrrev_i32_e32 v11, 31, v10
	v_lshl_add_u64 v[12:13], s[36:37], 0, v[12:13]
	v_lshlrev_b32_e32 v168, 9, v5
	v_lshl_add_u64 v[24:25], v[10:11], 1, v[0:1]
	v_lshl_add_u64 v[10:11], v[12:13], 0, v[168:169]
	v_mov_b32_e32 v5, v169
	v_lshl_add_u64 v[26:27], v[10:11], 0, v[4:5]
	global_load_dwordx4 v[10:13], v[24:25], off
	global_load_dwordx4 v[14:17], v[26:27], off
	v_or_b32_e32 v5, v23, v8
	v_add_u32_e32 v6, s8, v6
	v_lshlrev_b32_e32 v168, 1, v5
	v_cmp_lt_i32_e32 vcc, s6, v6
	v_add_u32_e32 v9, s40, v9
	s_or_b64 s[38:39], vcc, s[38:39]
	global_load_dwordx4 v[100:103], v[24:25], off offset:64
	global_load_dwordx4 v[18:21], v[26:27], off offset:64
	global_load_dwordx4 v[104:107], v[24:25], off offset:128
	global_load_dwordx4 v[108:111], v[26:27], off offset:128
	global_load_dwordx4 v[112:115], v[24:25], off offset:192
	global_load_dwordx4 v[116:119], v[26:27], off offset:192
	s_waitcnt vmcnt(6)
	v_mfma_f32_16x16x32_bf16 v[10:13], v[14:17], v[10:13], 0
	s_waitcnt vmcnt(4)
	v_mfma_f32_16x16x32_bf16 v[10:13], v[18:21], v[100:103], v[10:13]
	s_waitcnt vmcnt(2)
	v_mfma_f32_16x16x32_bf16 v[10:13], v[108:111], v[104:107], v[10:13]
	s_waitcnt vmcnt(0)
	v_mfma_f32_16x16x32_bf16 v[10:13], v[116:119], v[112:115], v[10:13]
	s_nop 7
	v_cvt_pk_bf16_f32 v10, v10, v11
	v_cvt_pk_bf16_f32 v11, v12, v13
	v_lshlrev_b32_e32 v12, 8, v22
	v_ashrrev_i32_e32 v13, 31, v12
	v_lshl_add_u64 v[12:13], v[12:13], 1, v[2:3]
	v_lshl_add_u64 v[12:13], v[12:13], 0, v[168:169]
	global_store_dwordx2 v[12:13], v[10:11], off
	s_andn2_b64 exec, exec, s[38:39]
	s_cbranch_execnz .LBB0_348

.LBB0_808:
	v_ashrrev_i32_e32 v6, 4, v8
	v_lshlrev_b32_e32 v24, 8, v6
	v_ashrrev_i32_e32 v7, 31, v6
	v_and_b32_e32 v30, 0xf0, v11
	v_ashrrev_i32_e32 v25, 31, v24
	v_lshlrev_b64 v[6:7], 17, v[6:7]
	v_or_b32_e32 v5, v30, v9
	v_lshl_add_u64 v[12:13], s[36:37], 0, v[6:7]
	v_lshlrev_b64 v[6:7], 1, v[24:25]
	v_lshlrev_b32_e32 v168, 9, v5
	v_lshl_add_u64 v[26:27], v[0:1], 0, v[6:7]
	v_lshl_add_u64 v[12:13], v[12:13], 0, v[168:169]
	v_mov_b32_e32 v5, v169
	v_lshl_add_u64 v[28:29], v[12:13], 0, v[4:5]
	global_load_dwordx4 v[12:15], v[26:27], off
	global_load_dwordx4 v[16:19], v[28:29], off
	v_or_b32_e32 v5, v30, v10
	v_lshlrev_b32_e32 v168, 2, v5
	v_add_u32_e32 v8, s4, v8
	v_lshl_add_u64 v[6:7], v[2:3], 0, v[6:7]
	v_cmp_lt_i32_e32 vcc, 63, v8
	v_add_u32_e32 v11, s42, v11
	s_or_b64 s[0:1], vcc, s[0:1]
	global_load_dwordx4 v[100:103], v[26:27], off offset:64
	global_load_dwordx4 v[20:23], v[28:29], off offset:64
	global_load_dwordx4 v[104:107], v[26:27], off offset:128
	global_load_dwordx4 v[108:111], v[28:29], off offset:128
	global_load_dwordx4 v[112:115], v[26:27], off offset:192
	global_load_dwordx4 v[116:119], v[28:29], off offset:192
	global_load_dwordx4 v[120:123], v[26:27], off offset:256
	global_load_dwordx4 v[124:127], v[28:29], off offset:256
	global_load_dwordx4 v[128:131], v[26:27], off offset:320
	global_load_dwordx4 v[132:135], v[28:29], off offset:320
	global_load_dwordx4 v[136:139], v[26:27], off offset:384
	global_load_dwordx4 v[140:143], v[28:29], off offset:384
	global_load_dwordx4 v[144:147], v[26:27], off offset:448
	global_load_dwordx4 v[148:151], v[28:29], off offset:448
	s_waitcnt vmcnt(14)
	v_mfma_f32_16x16x32_bf16 v[12:15], v[16:19], v[12:15], 0
	s_waitcnt vmcnt(12)
	v_mfma_f32_16x16x32_bf16 v[12:15], v[20:23], v[100:103], v[12:15]
	s_waitcnt vmcnt(10)
	v_mfma_f32_16x16x32_bf16 v[12:15], v[108:111], v[104:107], v[12:15]
	s_waitcnt vmcnt(8)
	v_mfma_f32_16x16x32_bf16 v[12:15], v[116:119], v[112:115], v[12:15]
	s_waitcnt vmcnt(6)
	v_mfma_f32_16x16x32_bf16 v[12:15], v[124:127], v[120:123], v[12:15]
	s_waitcnt vmcnt(4)
	v_mfma_f32_16x16x32_bf16 v[12:15], v[132:135], v[128:131], v[12:15]
	s_waitcnt vmcnt(2)
	v_mfma_f32_16x16x32_bf16 v[12:15], v[140:143], v[136:139], v[12:15]
	s_waitcnt vmcnt(0)
	v_mfma_f32_16x16x32_bf16 v[12:15], v[148:151], v[144:147], v[12:15]
	v_lshl_add_u64 v[16:17], v[24:25], 2, s[38:39]
	v_lshl_add_u64 v[16:17], v[16:17], 0, v[168:169]
	global_load_dwordx4 v[16:19], v[16:17], off
	v_lshlrev_b32_e32 v168, 1, v5
	v_lshl_add_u64 v[6:7], v[6:7], 0, v[168:169]
	s_waitcnt vmcnt(0)
	s_nop 1
	v_pk_mul_f32 v[12:13], v[12:13], v[16:17]
	v_pk_mul_f32 v[14:15], v[14:15], v[18:19]
	v_cvt_pk_bf16_f32 v12, v12, v13
	v_cvt_pk_bf16_f32 v13, v14, v15
	global_store_dwordx2 v[6:7], v[12:13], off
	s_andn2_b64 exec, exec, s[0:1]
	s_cbranch_execnz .LBB0_808

.LBB0_880:
	v_ashrrev_i32_e32 v22, 3, v6
	v_ashrrev_i32_e32 v23, 31, v22
	v_lshlrev_b64 v[12:13], 17, v[22:23]
	v_and_b32_e32 v23, 0x70, v9
	v_lshlrev_b32_e32 v10, 8, v22
	v_or_b32_e32 v5, v23, v7
	v_ashrrev_i32_e32 v11, 31, v10
	v_lshl_add_u64 v[12:13], s[44:45], 0, v[12:13]
	v_lshlrev_b32_e32 v168, 9, v5
	v_lshl_add_u64 v[24:25], v[10:11], 1, v[0:1]
	v_lshl_add_u64 v[10:11], v[12:13], 0, v[168:169]
	v_mov_b32_e32 v5, v169
	v_lshl_add_u64 v[26:27], v[10:11], 0, v[4:5]
	global_load_dwordx4 v[10:13], v[24:25], off
	global_load_dwordx4 v[14:17], v[26:27], off
	v_or_b32_e32 v5, v23, v8
	v_add_u32_e32 v6, s6, v6
	s_movk_i32 s49, 0x7f
	v_lshlrev_b32_e32 v168, 1, v5
	v_cmp_lt_i32_e32 vcc, s49, v6
	v_add_u32_e32 v9, s48, v9
	s_or_b64 s[46:47], vcc, s[46:47]
	global_load_dwordx4 v[100:103], v[24:25], off offset:64
	global_load_dwordx4 v[18:21], v[26:27], off offset:64
	global_load_dwordx4 v[104:107], v[24:25], off offset:128
	global_load_dwordx4 v[108:111], v[26:27], off offset:128
	global_load_dwordx4 v[112:115], v[24:25], off offset:192
	global_load_dwordx4 v[116:119], v[26:27], off offset:192
	global_load_dwordx4 v[120:123], v[24:25], off offset:256
	global_load_dwordx4 v[124:127], v[26:27], off offset:256
	global_load_dwordx4 v[128:131], v[24:25], off offset:320
	global_load_dwordx4 v[132:135], v[26:27], off offset:320
	global_load_dwordx4 v[136:139], v[24:25], off offset:384
	global_load_dwordx4 v[140:143], v[26:27], off offset:384
	global_load_dwordx4 v[144:147], v[24:25], off offset:448
	global_load_dwordx4 v[148:151], v[26:27], off offset:448
	s_waitcnt vmcnt(14)
	v_mfma_f32_16x16x32_bf16 v[10:13], v[14:17], v[10:13], 0
	s_waitcnt vmcnt(12)
	v_mfma_f32_16x16x32_bf16 v[10:13], v[18:21], v[100:103], v[10:13]
	s_waitcnt vmcnt(10)
	v_mfma_f32_16x16x32_bf16 v[10:13], v[108:111], v[104:107], v[10:13]
	s_waitcnt vmcnt(8)
	v_mfma_f32_16x16x32_bf16 v[10:13], v[116:119], v[112:115], v[10:13]
	s_waitcnt vmcnt(6)
	v_mfma_f32_16x16x32_bf16 v[10:13], v[124:127], v[120:123], v[10:13]
	s_waitcnt vmcnt(4)
	v_mfma_f32_16x16x32_bf16 v[10:13], v[132:135], v[128:131], v[10:13]
	s_waitcnt vmcnt(2)
	v_mfma_f32_16x16x32_bf16 v[10:13], v[140:143], v[136:139], v[10:13]
	s_waitcnt vmcnt(0)
	v_mfma_f32_16x16x32_bf16 v[10:13], v[148:151], v[144:147], v[10:13]
	s_nop 7
	v_cvt_pk_bf16_f32 v10, v10, v11
	v_cvt_pk_bf16_f32 v11, v12, v13
	v_lshlrev_b32_e32 v12, 7, v22
	v_ashrrev_i32_e32 v13, 31, v12
	v_lshl_add_u64 v[12:13], v[12:13], 1, v[2:3]
	v_lshl_add_u64 v[12:13], v[12:13], 0, v[168:169]
	global_store_dwordx2 v[12:13], v[10:11], off
	s_andn2_b64 exec, exec, s[46:47]
	s_cbranch_execnz .LBB0_880

.LBB0_884:
	v_add_u32_e32 v16, s36, v26
	v_ashrrev_i32_e32 v17, 31, v16
	v_lshlrev_b64 v[16:17], 11, v[16:17]
	v_lshl_add_u64 v[34:35], v[20:21], 0, v[16:17]
	global_load_dwordx4 v[16:19], v[34:35], off
	global_load_dwordx4 v[30:33], v[34:35], off offset:64
	global_load_dwordx4 v[100:103], v[34:35], off offset:128
	global_load_dwordx4 v[104:107], v[34:35], off offset:192
	s_waitcnt vmcnt(3)
	v_mfma_f32_16x16x32_bf16 v[16:19], v[16:19], v[8:11], 0
	s_waitcnt vmcnt(2)
	v_mfma_f32_16x16x32_bf16 v[16:19], v[30:33], v[0:3], v[16:19]
	s_waitcnt vmcnt(1)
	v_mfma_f32_16x16x32_bf16 v[16:19], v[100:103], v[4:7], v[16:19]
	s_waitcnt vmcnt(0)
	v_mfma_f32_16x16x32_bf16 v[16:19], v[104:107], v[12:15], v[16:19]
	s_nop 7
	ds_write_b128 v28, v[16:19]
	s_waitcnt lgkmcnt(0)
	s_barrier
	s_and_saveexec_b64 s[0:1], vcc
	s_cbranch_execz .LBB0_883
	ds_read_b128 v[30:33], v28 offset:1024
	s_waitcnt lgkmcnt(0)
	v_pk_add_f32 v[32:33], v[18:19], v[32:33]
	v_pk_add_f32 v[30:31], v[16:17], v[30:31]
	ds_read_b128 v[16:19], v28 offset:2048
	s_waitcnt lgkmcnt(0)
	v_pk_add_f32 v[32:33], v[32:33], v[18:19]
	v_pk_add_f32 v[30:31], v[30:31], v[16:17]
	ds_read_b128 v[16:19], v28 offset:3072
	s_waitcnt lgkmcnt(0)
	v_pk_add_f32 v[32:33], v[32:33], v[18:19]
	v_pk_add_f32 v[30:31], v[30:31], v[16:17]
	ds_read_b128 v[16:19], v28 offset:4096
	s_waitcnt lgkmcnt(0)
	v_pk_add_f32 v[32:33], v[32:33], v[18:19]
	v_pk_add_f32 v[30:31], v[30:31], v[16:17]
	ds_read_b128 v[16:19], v28 offset:5120
	s_waitcnt lgkmcnt(0)
	v_pk_add_f32 v[32:33], v[32:33], v[18:19]
	v_pk_add_f32 v[30:31], v[30:31], v[16:17]
	ds_read_b128 v[16:19], v28 offset:6144
	s_waitcnt lgkmcnt(0)
	v_pk_add_f32 v[32:33], v[32:33], v[18:19]
	v_pk_add_f32 v[30:31], v[30:31], v[16:17]
	ds_read_b128 v[16:19], v28 offset:7168
	s_waitcnt lgkmcnt(0)
	v_pk_add_f32 v[16:17], v[30:31], v[16:17]
	v_add_u32_e32 v30, s36, v27
	v_ashrrev_i32_e32 v31, 31, v30
	v_pk_add_f32 v[18:19], v[32:33], v[18:19]
	v_lshl_add_u64 v[32:33], v[30:31], 1, v[22:23]
	global_load_dwordx2 v[32:33], v[32:33], off
	v_lshl_add_u64 v[30:31], v[30:31], 2, v[24:25]
	s_waitcnt vmcnt(0)
	v_lshlrev_b32_e32 v29, 16, v32
	v_mul_f32_e32 v29, 0xbfb8aa3b, v29
	v_exp_f32_e32 v29, v29
	s_nop 0
	v_add_f32_e32 v29, 1.0, v29
	v_rcp_f32_e32 v34, v29
	v_and_b32_e32 v29, 0xffff0000, v32
	v_mul_f32_e32 v29, 0xbfb8aa3b, v29
	v_exp_f32_e32 v29, v29
	s_nop 0
	v_add_f32_e32 v29, 1.0, v29
	v_rcp_f32_e32 v35, v29
	v_lshlrev_b32_e32 v29, 16, v33
	v_mul_f32_e32 v29, 0xbfb8aa3b, v29
	v_exp_f32_e32 v29, v29
	v_pk_mul_f32 v[16:17], v[16:17], v[34:35]
	v_add_f32_e32 v29, 1.0, v29
	v_rcp_f32_e32 v32, v29
	v_and_b32_e32 v29, 0xffff0000, v33
	v_mul_f32_e32 v29, 0xbfb8aa3b, v29
	v_exp_f32_e32 v29, v29
	s_nop 0
	v_add_f32_e32 v29, 1.0, v29
	v_rcp_f32_e32 v33, v29
	s_nop 0
	v_pk_mul_f32 v[18:19], v[18:19], v[32:33]
	global_store_dwordx4 v[30:31], v[16:19], off
	s_branch .LBB0_883
